# st4/st6/st8 (residual GEMMs): K-loop, last K-tile and staged-epilogue LDS writes rewritten for v_mfma_f32_16x16x32_bf16 (same bf16 operands, f32 accumulate)
# speedup vs baseline: 1.0224x; 1.0224x over previous
.LBB0_33:
	v_lshl_add_u64 v[142:143], v[0:1], 0, s[66:67]
	v_mov_b32_e32 v0, 0
	v_lshl_add_u64 v[128:129], v[14:15], 0, s[66:67]
	v_lshl_add_u64 v[130:131], v[12:13], 0, s[66:67]
	v_lshl_add_u64 v[132:133], v[10:11], 0, s[66:67]
	v_lshl_add_u64 v[134:135], v[8:9], 0, s[66:67]
	v_lshl_add_u64 v[136:137], v[6:7], 0, s[66:67]
	v_lshl_add_u64 v[138:139], v[4:5], 0, s[66:67]
	v_lshl_add_u64 v[140:141], v[2:3], 0, s[66:67]
	s_mov_b32 s0, 0
	s_mov_b64 s[2:3], 0
	v_mov_b32_e32 v1, v0
	v_mov_b32_e32 v2, v0
	v_mov_b32_e32 v3, v0
	v_mov_b32_e32 v4, v0
	v_mov_b32_e32 v5, v0
	v_mov_b32_e32 v6, v0
	v_mov_b32_e32 v7, v0
	v_mov_b32_e32 v8, v0
	v_mov_b32_e32 v9, v0
	v_mov_b32_e32 v10, v0
	v_mov_b32_e32 v11, v0
	v_mov_b32_e32 v12, v0
	v_mov_b32_e32 v13, v0
	v_mov_b32_e32 v14, v0
	v_mov_b32_e32 v15, v0
	v_mov_b32_e32 v16, v0
	v_mov_b32_e32 v17, v0
	v_mov_b32_e32 v18, v0
	v_mov_b32_e32 v19, v0
	v_mov_b32_e32 v20, v0
	v_mov_b32_e32 v21, v0
	v_mov_b32_e32 v22, v0
	v_mov_b32_e32 v23, v0
	v_mov_b32_e32 v24, v0
	v_mov_b32_e32 v25, v0
	v_mov_b32_e32 v26, v0
	v_mov_b32_e32 v27, v0
	v_mov_b32_e32 v28, v0
	v_mov_b32_e32 v29, v0
	v_mov_b32_e32 v30, v0
	v_mov_b32_e32 v31, v0
	v_mov_b32_e32 v32, v0
	v_mov_b32_e32 v33, v0
	v_mov_b32_e32 v34, v0
	v_mov_b32_e32 v35, v0
	v_mov_b32_e32 v36, v0
	v_mov_b32_e32 v37, v0
	v_mov_b32_e32 v38, v0
	v_mov_b32_e32 v39, v0
	v_mov_b32_e32 v40, v0
	v_mov_b32_e32 v41, v0
	v_mov_b32_e32 v42, v0
	v_mov_b32_e32 v43, v0
	v_mov_b32_e32 v44, v0
	v_mov_b32_e32 v45, v0
	v_mov_b32_e32 v46, v0
	v_mov_b32_e32 v47, v0
	v_mov_b32_e32 v48, v0
	v_mov_b32_e32 v49, v0
	v_mov_b32_e32 v50, v0
	v_mov_b32_e32 v51, v0
	v_mov_b32_e32 v52, v0
	v_mov_b32_e32 v53, v0
	v_mov_b32_e32 v54, v0
	v_mov_b32_e32 v55, v0
	v_mov_b32_e32 v56, v0
	v_mov_b32_e32 v57, v0
	v_mov_b32_e32 v58, v0
	v_mov_b32_e32 v59, v0
	v_mov_b32_e32 v60, v0
	v_mov_b32_e32 v61, v0
	v_mov_b32_e32 v62, v0
	v_mov_b32_e32 v63, v0
	v_mov_b32_e32 v64, v0
	v_mov_b32_e32 v65, v0
	v_mov_b32_e32 v66, v0
	v_mov_b32_e32 v67, v0
	v_mov_b32_e32 v68, v0
	v_mov_b32_e32 v69, v0
	v_mov_b32_e32 v70, v0
	v_mov_b32_e32 v71, v0
	v_mov_b32_e32 v72, v0
	v_mov_b32_e32 v73, v0
	v_mov_b32_e32 v74, v0
	v_mov_b32_e32 v75, v0
	v_mov_b32_e32 v76, v0
	v_mov_b32_e32 v77, v0
	v_mov_b32_e32 v78, v0
	v_mov_b32_e32 v79, v0
	v_mov_b32_e32 v80, v0
	v_mov_b32_e32 v81, v0
	v_mov_b32_e32 v82, v0
	v_mov_b32_e32 v83, v0
	v_mov_b32_e32 v84, v0
	v_mov_b32_e32 v85, v0
	v_mov_b32_e32 v86, v0
	v_mov_b32_e32 v87, v0
	v_mov_b32_e32 v88, v0
	v_mov_b32_e32 v89, v0
	v_mov_b32_e32 v90, v0
	v_mov_b32_e32 v91, v0
	v_mov_b32_e32 v92, v0
	v_mov_b32_e32 v93, v0
	v_mov_b32_e32 v94, v0
	v_mov_b32_e32 v95, v0
	v_mov_b32_e32 v96, v0
	v_mov_b32_e32 v97, v0
	v_mov_b32_e32 v98, v0
	v_mov_b32_e32 v99, v0
	v_mov_b32_e32 v100, v0
	v_mov_b32_e32 v101, v0
	v_mov_b32_e32 v102, v0
	v_mov_b32_e32 v103, v0
	v_mov_b32_e32 v104, v0
	v_mov_b32_e32 v105, v0
	v_mov_b32_e32 v106, v0
	v_mov_b32_e32 v107, v0
	v_mov_b32_e32 v108, v0
	v_mov_b32_e32 v109, v0
	v_mov_b32_e32 v110, v0
	v_mov_b32_e32 v111, v0
	v_mov_b32_e32 v112, v0
	v_mov_b32_e32 v113, v0
	v_mov_b32_e32 v114, v0
	v_mov_b32_e32 v115, v0
	v_mov_b32_e32 v116, v0
	v_mov_b32_e32 v117, v0
	v_mov_b32_e32 v118, v0
	v_mov_b32_e32 v119, v0
	v_mov_b32_e32 v120, v0
	v_mov_b32_e32 v121, v0
	v_mov_b32_e32 v122, v0
	v_mov_b32_e32 v123, v0
	v_mov_b32_e32 v124, v0
	v_mov_b32_e32 v125, v0
	v_mov_b32_e32 v126, v0
	v_mov_b32_e32 v127, v0
	v_and_b32_e32 v250, 15, v184
	v_bfe_u32 v251, v184, 4, 2
	v_bfe_u32 v252, v184, 1, 3
	v_xor_b32_e32 v251, v251, v252
	v_lshlrev_b32_e32 v251, 4, v251
	v_lshl_add_u32 v251, v250, 7, v251
	v_lshrrev_b32_e32 v252, 8, v184
	v_lshl_add_u32 v248, v252, 14, v251
	v_bfe_u32 v252, v184, 6, 2
	v_lshl_add_u32 v249, v252, 13, v251
	v_add_u32_e32 v249, 0x8000, v249
.LBB0_34:
	s_add_i32 s1, s0, 0x10000
	s_and_b32 s13, s1, 0x10000
	s_and_b32 s0, s0, 0x10000
	s_add_i32 s0, s0, 16
	v_add_u32_e32 v190, s13, v210
	s_nop 0
	v_readfirstlane_b32 s13, v190
	s_waitcnt vmcnt(0)
	s_barrier
	v_add_u32_e32 v251, s0, v249
	ds_read_b128 v[150:153], v251
	ds_read_b128 v[154:157], v251 offset:2048
	ds_read_b128 v[158:161], v251 offset:4096
	ds_read_b128 v[162:165], v251 offset:6144
	v_add_u32_e32 v250, s0, v248
	ds_read_b128 v[170:173], v250
	ds_read_b128 v[174:177], v250 offset:2048
	ds_read_b128 v[236:239], v250 offset:4096
	ds_read_b128 v[240:243], v250 offset:6144
	v_lshl_add_u64 v[178:179], v[142:143], 0, s[2:3]
	s_mov_b32 m0, s13
	s_nop 0
	global_load_lds_dwordx4 v[178:179], off
	s_waitcnt lgkmcnt(3)
	v_mfma_f32_16x16x32_bf16 v[0:3], v[150:153], v[170:173], v[0:3]
	v_mfma_f32_16x16x32_bf16 v[32:35], v[154:157], v[170:173], v[32:35]
	v_lshl_add_u64 v[178:179], v[140:141], 0, s[2:3]
	s_add_i32 s14, s13, 0x2000
	s_mov_b32 m0, s14
	s_nop 0
	global_load_lds_dwordx4 v[178:179], off
	v_mfma_f32_16x16x32_bf16 v[64:67], v[158:161], v[170:173], v[64:67]
	v_mfma_f32_16x16x32_bf16 v[96:99], v[162:165], v[170:173], v[96:99]
	s_waitcnt lgkmcnt(2)
	v_mfma_f32_16x16x32_bf16 v[4:7], v[150:153], v[174:177], v[4:7]
	v_mfma_f32_16x16x32_bf16 v[36:39], v[154:157], v[174:177], v[36:39]
	v_lshl_add_u64 v[178:179], v[138:139], 0, s[2:3]
	s_add_i32 s14, s13, 0x4000
	s_mov_b32 m0, s14
	s_nop 0
	global_load_lds_dwordx4 v[178:179], off
	v_mfma_f32_16x16x32_bf16 v[68:71], v[158:161], v[174:177], v[68:71]
	v_mfma_f32_16x16x32_bf16 v[100:103], v[162:165], v[174:177], v[100:103]
	s_waitcnt lgkmcnt(1)
	v_mfma_f32_16x16x32_bf16 v[8:11], v[150:153], v[236:239], v[8:11]
	v_mfma_f32_16x16x32_bf16 v[40:43], v[154:157], v[236:239], v[40:43]
	v_lshl_add_u64 v[178:179], v[136:137], 0, s[2:3]
	s_add_i32 s14, s13, 0x6000
	s_mov_b32 m0, s14
	s_nop 0
	global_load_lds_dwordx4 v[178:179], off
	v_mfma_f32_16x16x32_bf16 v[72:75], v[158:161], v[236:239], v[72:75]
	v_mfma_f32_16x16x32_bf16 v[104:107], v[162:165], v[236:239], v[104:107]
	s_waitcnt lgkmcnt(0)
	v_mfma_f32_16x16x32_bf16 v[12:15], v[150:153], v[240:243], v[12:15]
	v_mfma_f32_16x16x32_bf16 v[44:47], v[154:157], v[240:243], v[44:47]
	v_lshl_add_u64 v[178:179], v[134:135], 0, s[2:3]
	s_add_i32 s14, s13, 0x8000
	s_mov_b32 m0, s14
	s_nop 0
	global_load_lds_dwordx4 v[178:179], off
	v_mfma_f32_16x16x32_bf16 v[76:79], v[158:161], v[240:243], v[76:79]
	v_mfma_f32_16x16x32_bf16 v[108:111], v[162:165], v[240:243], v[108:111]
	ds_read_b128 v[170:173], v250 offset:8192
	ds_read_b128 v[174:177], v250 offset:10240
	ds_read_b128 v[236:239], v250 offset:12288
	ds_read_b128 v[240:243], v250 offset:14336
	s_waitcnt lgkmcnt(3)
	v_mfma_f32_16x16x32_bf16 v[16:19], v[150:153], v[170:173], v[16:19]
	v_mfma_f32_16x16x32_bf16 v[48:51], v[154:157], v[170:173], v[48:51]
	v_lshl_add_u64 v[178:179], v[132:133], 0, s[2:3]
	s_add_i32 s14, s13, 0xa000
	s_mov_b32 m0, s14
	s_nop 0
	global_load_lds_dwordx4 v[178:179], off
	v_mfma_f32_16x16x32_bf16 v[80:83], v[158:161], v[170:173], v[80:83]
	v_mfma_f32_16x16x32_bf16 v[112:115], v[162:165], v[170:173], v[112:115]
	s_waitcnt lgkmcnt(2)
	v_mfma_f32_16x16x32_bf16 v[20:23], v[150:153], v[174:177], v[20:23]
	v_mfma_f32_16x16x32_bf16 v[52:55], v[154:157], v[174:177], v[52:55]
	v_lshl_add_u64 v[178:179], v[130:131], 0, s[2:3]
	s_add_i32 s14, s13, 0xc000
	s_mov_b32 m0, s14
	s_nop 0
	global_load_lds_dwordx4 v[178:179], off
	v_mfma_f32_16x16x32_bf16 v[84:87], v[158:161], v[174:177], v[84:87]
	v_mfma_f32_16x16x32_bf16 v[116:119], v[162:165], v[174:177], v[116:119]
	s_waitcnt lgkmcnt(1)
	v_mfma_f32_16x16x32_bf16 v[24:27], v[150:153], v[236:239], v[24:27]
	v_mfma_f32_16x16x32_bf16 v[56:59], v[154:157], v[236:239], v[56:59]
	v_lshl_add_u64 v[178:179], v[128:129], 0, s[2:3]
	s_add_i32 s14, s13, 0xe000
	s_mov_b32 m0, s14
	s_nop 0
	global_load_lds_dwordx4 v[178:179], off
	s_add_u32 s2, s2, 0x80
	s_addc_u32 s3, s3, 0
	s_cmpk_lg_i32 s2, 0x1f80
	v_mfma_f32_16x16x32_bf16 v[88:91], v[158:161], v[236:239], v[88:91]
	v_mfma_f32_16x16x32_bf16 v[120:123], v[162:165], v[236:239], v[120:123]
	s_waitcnt lgkmcnt(0)
	v_mfma_f32_16x16x32_bf16 v[28:31], v[150:153], v[240:243], v[28:31]
	v_mfma_f32_16x16x32_bf16 v[60:63], v[154:157], v[240:243], v[60:63]
	v_mfma_f32_16x16x32_bf16 v[92:95], v[158:161], v[240:243], v[92:95]
	v_mfma_f32_16x16x32_bf16 v[124:127], v[162:165], v[240:243], v[124:127]
	v_xor_b32_e32 v251, 64, v249
	v_add_u32_e32 v251, s0, v251
	ds_read_b128 v[150:153], v251
	ds_read_b128 v[154:157], v251 offset:2048
	ds_read_b128 v[158:161], v251 offset:4096
	ds_read_b128 v[162:165], v251 offset:6144
	v_xor_b32_e32 v250, 64, v248
	v_add_u32_e32 v250, s0, v250
	ds_read_b128 v[170:173], v250
	ds_read_b128 v[174:177], v250 offset:2048
	ds_read_b128 v[236:239], v250 offset:4096
	ds_read_b128 v[240:243], v250 offset:6144
	s_waitcnt lgkmcnt(3)
	v_mfma_f32_16x16x32_bf16 v[0:3], v[150:153], v[170:173], v[0:3]
	v_mfma_f32_16x16x32_bf16 v[32:35], v[154:157], v[170:173], v[32:35]
	v_mfma_f32_16x16x32_bf16 v[64:67], v[158:161], v[170:173], v[64:67]
	v_mfma_f32_16x16x32_bf16 v[96:99], v[162:165], v[170:173], v[96:99]
	s_waitcnt lgkmcnt(2)
	v_mfma_f32_16x16x32_bf16 v[4:7], v[150:153], v[174:177], v[4:7]
	v_mfma_f32_16x16x32_bf16 v[36:39], v[154:157], v[174:177], v[36:39]
	v_mfma_f32_16x16x32_bf16 v[68:71], v[158:161], v[174:177], v[68:71]
	v_mfma_f32_16x16x32_bf16 v[100:103], v[162:165], v[174:177], v[100:103]
	s_waitcnt lgkmcnt(1)
	v_mfma_f32_16x16x32_bf16 v[8:11], v[150:153], v[236:239], v[8:11]
	v_mfma_f32_16x16x32_bf16 v[40:43], v[154:157], v[236:239], v[40:43]
	v_mfma_f32_16x16x32_bf16 v[72:75], v[158:161], v[236:239], v[72:75]
	v_mfma_f32_16x16x32_bf16 v[104:107], v[162:165], v[236:239], v[104:107]
	s_waitcnt lgkmcnt(0)
	v_mfma_f32_16x16x32_bf16 v[12:15], v[150:153], v[240:243], v[12:15]
	v_mfma_f32_16x16x32_bf16 v[44:47], v[154:157], v[240:243], v[44:47]
	v_mfma_f32_16x16x32_bf16 v[76:79], v[158:161], v[240:243], v[76:79]
	v_mfma_f32_16x16x32_bf16 v[108:111], v[162:165], v[240:243], v[108:111]
	ds_read_b128 v[170:173], v250 offset:8192
	ds_read_b128 v[174:177], v250 offset:10240
	ds_read_b128 v[236:239], v250 offset:12288
	ds_read_b128 v[240:243], v250 offset:14336
	s_waitcnt lgkmcnt(3)
	v_mfma_f32_16x16x32_bf16 v[16:19], v[150:153], v[170:173], v[16:19]
	v_mfma_f32_16x16x32_bf16 v[48:51], v[154:157], v[170:173], v[48:51]
	v_mfma_f32_16x16x32_bf16 v[80:83], v[158:161], v[170:173], v[80:83]
	v_mfma_f32_16x16x32_bf16 v[112:115], v[162:165], v[170:173], v[112:115]
	s_waitcnt lgkmcnt(2)
	v_mfma_f32_16x16x32_bf16 v[20:23], v[150:153], v[174:177], v[20:23]
	v_mfma_f32_16x16x32_bf16 v[52:55], v[154:157], v[174:177], v[52:55]
	v_mfma_f32_16x16x32_bf16 v[84:87], v[158:161], v[174:177], v[84:87]
	v_mfma_f32_16x16x32_bf16 v[116:119], v[162:165], v[174:177], v[116:119]
	s_waitcnt lgkmcnt(1)
	v_mfma_f32_16x16x32_bf16 v[24:27], v[150:153], v[236:239], v[24:27]
	v_mfma_f32_16x16x32_bf16 v[56:59], v[154:157], v[236:239], v[56:59]
	v_mfma_f32_16x16x32_bf16 v[88:91], v[158:161], v[236:239], v[88:91]
	v_mfma_f32_16x16x32_bf16 v[120:123], v[162:165], v[236:239], v[120:123]
	s_waitcnt lgkmcnt(0)
	v_mfma_f32_16x16x32_bf16 v[28:31], v[150:153], v[240:243], v[28:31]
	v_mfma_f32_16x16x32_bf16 v[60:63], v[154:157], v[240:243], v[60:63]
	v_mfma_f32_16x16x32_bf16 v[92:95], v[158:161], v[240:243], v[92:95]
	v_mfma_f32_16x16x32_bf16 v[124:127], v[162:165], v[240:243], v[124:127]
	s_mov_b32 s0, s1
	s_cbranch_scc1 .LBB0_34
	s_add_i32 s23, s23, s78
	s_cmpk_gt_i32 s23, 0xff
	s_waitcnt vmcnt(0)
	s_barrier
	s_cselect_b64 s[2:3], -1, 0
	s_and_b64 vcc, exec, s[2:3]
	s_cbranch_vccnz .LBB0_37
	s_lshl_b32 s0, s23, 3
	s_lshr_b32 s1, s23, 5
	s_and_b32 s0, s0, 56
	s_add_i32 s0, s0, s1
	s_lshl_b32 s10, s23, 5
	v_lshl_add_u32 v130, s0, 8, v207
	s_and_b32 s10, s10, 0x300
	v_ashrrev_i32_e32 v131, 31, v130
	v_lshlrev_b64 v[132:133], 13, v[130:131]
	s_cmp_lg_u32 16, -1
	v_lshl_add_u64 v[132:133], v[146:147], 0, v[132:133]
	v_readfirstlane_b32 s0, v209
	s_cselect_b32 s1, 16, 0
	s_add_i32 s0, s0, s1
	s_mov_b32 s1, m0
	s_mov_b32 m0, s0
	s_nop 0
	global_load_lds_dwordx4 v[132:133], off
	s_mov_b32 m0, s1
	v_add_u32_e32 v132, 64, v130
	v_ashrrev_i32_e32 v133, 31, v132
	v_lshlrev_b64 v[132:133], 13, v[132:133]
	v_lshl_add_u64 v[132:133], v[146:147], 0, v[132:133]
	v_add_u32_e32 v128, s10, v208
	s_add_i32 s1, s0, 0x2000
	s_mov_b32 s10, m0
	s_mov_b32 m0, s1
	s_nop 0
	global_load_lds_dwordx4 v[132:133], off
	s_mov_b32 m0, s10
	v_add_u32_e32 v132, 0x80, v130
	v_ashrrev_i32_e32 v133, 31, v132
	v_add_u32_e32 v130, 0xc0, v130
	v_lshlrev_b64 v[132:133], 13, v[132:133]
	v_ashrrev_i32_e32 v131, 31, v130
	v_lshl_add_u64 v[132:133], v[146:147], 0, v[132:133]
	s_add_i32 s1, s0, 0x4000
	s_mov_b32 s10, m0
	s_mov_b32 m0, s1
	s_nop 0
	global_load_lds_dwordx4 v[132:133], off
	s_mov_b32 m0, s10
	v_lshlrev_b64 v[130:131], 13, v[130:131]
	v_ashrrev_i32_e32 v129, 31, v128
	v_lshl_add_u64 v[130:131], v[146:147], 0, v[130:131]
	s_add_i32 s1, s0, 0x6000
	s_mov_b32 s10, m0
	s_mov_b32 m0, s1
	s_nop 0
	global_load_lds_dwordx4 v[130:131], off
	s_mov_b32 m0, s10
	v_lshlrev_b64 v[128:129], 13, v[128:129]
	v_lshl_add_u64 v[128:129], v[144:145], 0, v[128:129]
	s_mov_b64 s[10:11], 0x200000
	v_lshl_add_u64 v[130:131], v[128:129], 0, s[10:11]
	s_add_i32 s1, s0, 0x8000
	s_mov_b32 s10, m0
	s_mov_b32 m0, s1
	s_nop 0
	global_load_lds_dwordx4 v[130:131], off
	s_mov_b32 m0, s10
	s_mov_b64 s[10:11], 0x280000
	v_lshl_add_u64 v[130:131], v[128:129], 0, s[10:11]
	s_add_i32 s1, s0, 0xa000
	s_mov_b32 s10, m0
	s_mov_b32 m0, s1
	s_nop 0
	global_load_lds_dwordx4 v[130:131], off
	s_mov_b32 m0, s10
	s_mov_b64 s[10:11], 0x300000
	v_lshl_add_u64 v[130:131], v[128:129], 0, s[10:11]
	s_add_i32 s1, s0, 0xc000
	s_mov_b32 s10, m0
	s_mov_b32 m0, s1
	s_nop 0
	global_load_lds_dwordx4 v[130:131], off
	s_mov_b32 m0, s10
	s_mov_b64 s[10:11], 0x380000
	v_lshl_add_u64 v[128:129], v[128:129], 0, s[10:11]
	s_add_i32 s0, s0, 0xe000
	s_mov_b32 s1, m0
	s_mov_b32 m0, s0
	s_nop 0
	global_load_lds_dwordx4 v[128:129], off
	s_mov_b32 m0, s1
	s_mov_b64 s[10:11], -1
.LBB0_37:
	v_add_u32_e32 v251, 0x10010, v249
	ds_read_b128 v[150:153], v251
	ds_read_b128 v[154:157], v251 offset:2048
	ds_read_b128 v[158:161], v251 offset:4096
	ds_read_b128 v[162:165], v251 offset:6144
	v_add_u32_e32 v250, 0x10010, v248
	ds_read_b128 v[170:173], v250
	ds_read_b128 v[174:177], v250 offset:2048
	ds_read_b128 v[236:239], v250 offset:4096
	ds_read_b128 v[240:243], v250 offset:6144
	s_waitcnt lgkmcnt(3)
	v_mfma_f32_16x16x32_bf16 v[0:3], v[150:153], v[170:173], v[0:3]
	v_mfma_f32_16x16x32_bf16 v[32:35], v[154:157], v[170:173], v[32:35]
	v_mfma_f32_16x16x32_bf16 v[64:67], v[158:161], v[170:173], v[64:67]
	v_mfma_f32_16x16x32_bf16 v[96:99], v[162:165], v[170:173], v[96:99]
	s_waitcnt lgkmcnt(2)
	v_mfma_f32_16x16x32_bf16 v[4:7], v[150:153], v[174:177], v[4:7]
	v_mfma_f32_16x16x32_bf16 v[36:39], v[154:157], v[174:177], v[36:39]
	v_mfma_f32_16x16x32_bf16 v[68:71], v[158:161], v[174:177], v[68:71]
	v_mfma_f32_16x16x32_bf16 v[100:103], v[162:165], v[174:177], v[100:103]
	s_waitcnt lgkmcnt(1)
	v_mfma_f32_16x16x32_bf16 v[8:11], v[150:153], v[236:239], v[8:11]
	v_mfma_f32_16x16x32_bf16 v[40:43], v[154:157], v[236:239], v[40:43]
	v_mfma_f32_16x16x32_bf16 v[72:75], v[158:161], v[236:239], v[72:75]
	v_mfma_f32_16x16x32_bf16 v[104:107], v[162:165], v[236:239], v[104:107]
	s_waitcnt lgkmcnt(0)
	v_mfma_f32_16x16x32_bf16 v[12:15], v[150:153], v[240:243], v[12:15]
	v_mfma_f32_16x16x32_bf16 v[44:47], v[154:157], v[240:243], v[44:47]
	v_mfma_f32_16x16x32_bf16 v[76:79], v[158:161], v[240:243], v[76:79]
	v_mfma_f32_16x16x32_bf16 v[108:111], v[162:165], v[240:243], v[108:111]
	ds_read_b128 v[170:173], v250 offset:8192
	ds_read_b128 v[174:177], v250 offset:10240
	ds_read_b128 v[236:239], v250 offset:12288
	ds_read_b128 v[240:243], v250 offset:14336
	s_waitcnt lgkmcnt(3)
	v_mfma_f32_16x16x32_bf16 v[16:19], v[150:153], v[170:173], v[16:19]
	v_mfma_f32_16x16x32_bf16 v[48:51], v[154:157], v[170:173], v[48:51]
	v_mfma_f32_16x16x32_bf16 v[80:83], v[158:161], v[170:173], v[80:83]
	v_mfma_f32_16x16x32_bf16 v[112:115], v[162:165], v[170:173], v[112:115]
	s_waitcnt lgkmcnt(2)
	v_mfma_f32_16x16x32_bf16 v[20:23], v[150:153], v[174:177], v[20:23]
	v_mfma_f32_16x16x32_bf16 v[52:55], v[154:157], v[174:177], v[52:55]
	v_mfma_f32_16x16x32_bf16 v[84:87], v[158:161], v[174:177], v[84:87]
	v_mfma_f32_16x16x32_bf16 v[116:119], v[162:165], v[174:177], v[116:119]
	s_waitcnt lgkmcnt(1)
	v_mfma_f32_16x16x32_bf16 v[24:27], v[150:153], v[236:239], v[24:27]
	v_mfma_f32_16x16x32_bf16 v[56:59], v[154:157], v[236:239], v[56:59]
	v_mfma_f32_16x16x32_bf16 v[88:91], v[158:161], v[236:239], v[88:91]
	v_mfma_f32_16x16x32_bf16 v[120:123], v[162:165], v[236:239], v[120:123]
	s_waitcnt lgkmcnt(0)
	v_mfma_f32_16x16x32_bf16 v[28:31], v[150:153], v[240:243], v[28:31]
	v_mfma_f32_16x16x32_bf16 v[60:63], v[154:157], v[240:243], v[60:63]
	v_mfma_f32_16x16x32_bf16 v[92:95], v[158:161], v[240:243], v[92:95]
	v_mfma_f32_16x16x32_bf16 v[124:127], v[162:165], v[240:243], v[124:127]
	v_xor_b32_e32 v251, 64, v249
	v_add_u32_e32 v251, 0x10010, v251
	ds_read_b128 v[150:153], v251
	ds_read_b128 v[154:157], v251 offset:2048
	ds_read_b128 v[158:161], v251 offset:4096
	ds_read_b128 v[162:165], v251 offset:6144
	v_xor_b32_e32 v250, 64, v248
	v_add_u32_e32 v250, 0x10010, v250
	ds_read_b128 v[170:173], v250
	ds_read_b128 v[174:177], v250 offset:2048
	ds_read_b128 v[236:239], v250 offset:4096
	ds_read_b128 v[240:243], v250 offset:6144
	s_waitcnt lgkmcnt(3)
	v_mfma_f32_16x16x32_bf16 v[0:3], v[150:153], v[170:173], v[0:3]
	v_mfma_f32_16x16x32_bf16 v[32:35], v[154:157], v[170:173], v[32:35]
	v_mfma_f32_16x16x32_bf16 v[64:67], v[158:161], v[170:173], v[64:67]
	v_mfma_f32_16x16x32_bf16 v[96:99], v[162:165], v[170:173], v[96:99]
	s_waitcnt lgkmcnt(2)
	v_mfma_f32_16x16x32_bf16 v[4:7], v[150:153], v[174:177], v[4:7]
	v_mfma_f32_16x16x32_bf16 v[36:39], v[154:157], v[174:177], v[36:39]
	v_mfma_f32_16x16x32_bf16 v[68:71], v[158:161], v[174:177], v[68:71]
	v_mfma_f32_16x16x32_bf16 v[100:103], v[162:165], v[174:177], v[100:103]
	s_waitcnt lgkmcnt(1)
	v_mfma_f32_16x16x32_bf16 v[8:11], v[150:153], v[236:239], v[8:11]
	v_mfma_f32_16x16x32_bf16 v[40:43], v[154:157], v[236:239], v[40:43]
	v_mfma_f32_16x16x32_bf16 v[72:75], v[158:161], v[236:239], v[72:75]
	v_mfma_f32_16x16x32_bf16 v[104:107], v[162:165], v[236:239], v[104:107]
	s_waitcnt lgkmcnt(0)
	v_mfma_f32_16x16x32_bf16 v[12:15], v[150:153], v[240:243], v[12:15]
	v_mfma_f32_16x16x32_bf16 v[44:47], v[154:157], v[240:243], v[44:47]
	v_mfma_f32_16x16x32_bf16 v[76:79], v[158:161], v[240:243], v[76:79]
	v_mfma_f32_16x16x32_bf16 v[108:111], v[162:165], v[240:243], v[108:111]
	ds_read_b128 v[170:173], v250 offset:8192
	ds_read_b128 v[174:177], v250 offset:10240
	ds_read_b128 v[236:239], v250 offset:12288
	ds_read_b128 v[240:243], v250 offset:14336
	s_waitcnt lgkmcnt(0)
	s_barrier
	v_mfma_f32_16x16x32_bf16 v[16:19], v[150:153], v[170:173], v[16:19]
	v_mfma_f32_16x16x32_bf16 v[48:51], v[154:157], v[170:173], v[48:51]
	v_mfma_f32_16x16x32_bf16 v[80:83], v[158:161], v[170:173], v[80:83]
	v_mfma_f32_16x16x32_bf16 v[112:115], v[162:165], v[170:173], v[112:115]
	v_mfma_f32_16x16x32_bf16 v[20:23], v[150:153], v[174:177], v[20:23]
	v_mfma_f32_16x16x32_bf16 v[52:55], v[154:157], v[174:177], v[52:55]
	v_mfma_f32_16x16x32_bf16 v[84:87], v[158:161], v[174:177], v[84:87]
	v_mfma_f32_16x16x32_bf16 v[116:119], v[162:165], v[174:177], v[116:119]
	v_mfma_f32_16x16x32_bf16 v[24:27], v[150:153], v[236:239], v[24:27]
	v_mfma_f32_16x16x32_bf16 v[56:59], v[154:157], v[236:239], v[56:59]
	v_mfma_f32_16x16x32_bf16 v[88:91], v[158:161], v[236:239], v[88:91]
	v_mfma_f32_16x16x32_bf16 v[120:123], v[162:165], v[236:239], v[120:123]
	v_mfma_f32_16x16x32_bf16 v[28:31], v[150:153], v[240:243], v[28:31]
	v_mfma_f32_16x16x32_bf16 v[60:63], v[154:157], v[240:243], v[60:63]
	v_mfma_f32_16x16x32_bf16 v[92:95], v[158:161], v[240:243], v[92:95]
	v_mfma_f32_16x16x32_bf16 v[124:127], v[162:165], v[240:243], v[124:127]
	s_lshl_b32 s52, s12, 2
	s_lshr_b32 s0, s12, 4
	s_add_u32 s0, s20, s0
	v_or_b32_e32 v236, s12, v213
	v_lshl_add_u64 v[166:167], v[148:149], 0, s[52:53]
	s_addc_u32 s1, s21, 0
	s_mov_b32 s12, 0
	v_or_b32_e32 v128, s27, v212
	v_add_u32_e32 v128, v128, v211
	v_add_u32_e32 v130, 16, v128
	v_ashrrev_i32_e32 v131, 31, v130
	v_lshlrev_b64 v[158:159], 12, v[130:131]
	v_add_u32_e32 v130, 20, v128
	v_ashrrev_i32_e32 v129, 31, v128
	v_ashrrev_i32_e32 v131, 31, v130
	v_lshlrev_b64 v[160:161], 12, v[130:131]
	v_add_u32_e32 v130, 24, v128
	v_ashrrev_i32_e32 v131, 31, v130
	v_lshlrev_b64 v[162:163], 12, v[130:131]
	v_lshlrev_b64 v[150:151], 12, v[128:129]
	v_or_b32_e32 v132, 4, v128
	v_ashrrev_i32_e32 v133, 31, v132
	v_lshlrev_b64 v[152:153], 12, v[132:133]
	v_or_b32_e32 v132, 8, v128
	v_ashrrev_i32_e32 v133, 31, v132
	v_lshlrev_b64 v[154:155], 12, v[132:133]
	v_or_b32_e32 v132, 12, v128
	v_add_u32_e32 v128, 28, v128
	v_ashrrev_i32_e32 v133, 31, v132
	v_ashrrev_i32_e32 v129, 31, v128
	v_lshlrev_b64 v[156:157], 12, v[132:133]
	v_lshlrev_b64 v[164:165], 12, v[128:129]
	s_branch .LBB0_39

.LBB0_39:
	s_lshl_b32 s52, s12, 6
	v_lshl_add_u64 v[176:177], s[52:53], 2, v[166:167]
	v_lshl_add_u64 v[128:129], v[176:177], 0, v[150:151]
	v_lshl_add_u64 v[132:133], v[176:177], 0, v[152:153]
	v_lshl_add_u64 v[136:137], v[176:177], 0, v[154:155]
	v_lshl_add_u64 v[140:141], v[176:177], 0, v[156:157]
	global_load_dwordx4 v[128:131], v[128:129], off
	s_nop 0
	global_load_dwordx4 v[132:135], v[132:133], off
	s_nop 0
	global_load_dwordx4 v[136:139], v[136:137], off
	s_nop 0
	global_load_dwordx4 v[140:143], v[140:141], off
	v_cmp_eq_u32_e32 vcc, s12, v181
	s_and_saveexec_b64 s[14:15], vcc
	s_cbranch_execz .LBB0_41
	v_and_b32_e32 v237, 15, v184
	v_bfe_u32 v238, v184, 4, 2
	v_lshrrev_b32_e32 v239, 8, v184
	v_lshlrev_b32_e32 v240, 8, v237
	v_lshl_add_u32 v240, v239, 15, v240
	v_add_u32_e32 v240, 0x10010, v240
	v_or_b32_e32 v241, 0, v238
	v_xor_b32_e32 v241, v241, v237
	v_lshl_add_u32 v168, v241, 4, v240
	v_or_b32_e32 v241, 4, v238
	v_xor_b32_e32 v241, v241, v237
	v_lshl_add_u32 v178, v241, 4, v240
	v_or_b32_e32 v241, 8, v238
	v_xor_b32_e32 v241, v241, v237
	v_lshl_add_u32 v179, v241, 4, v240
	v_or_b32_e32 v241, 12, v238
	v_xor_b32_e32 v241, v241, v237
	v_lshl_add_u32 v190, v241, 4, v240
	ds_write_b128 v168, v[0:3]
	ds_write_b128 v178, v[32:35]
	ds_write_b128 v179, v[64:67]
	ds_write_b128 v190, v[96:99]
	ds_write_b128 v168, v[4:7] offset:4096
	ds_write_b128 v178, v[36:39] offset:4096
	ds_write_b128 v179, v[68:71] offset:4096
	ds_write_b128 v190, v[100:103] offset:4096
	ds_write_b128 v168, v[8:11] offset:8192
	ds_write_b128 v178, v[40:43] offset:8192
	ds_write_b128 v179, v[72:75] offset:8192
	ds_write_b128 v190, v[104:107] offset:8192
	ds_write_b128 v168, v[12:15] offset:12288
	ds_write_b128 v178, v[44:47] offset:12288
	ds_write_b128 v179, v[76:79] offset:12288
	ds_write_b128 v190, v[108:111] offset:12288
	ds_write_b128 v168, v[16:19] offset:16384
	ds_write_b128 v178, v[48:51] offset:16384
	ds_write_b128 v179, v[80:83] offset:16384
	ds_write_b128 v190, v[112:115] offset:16384
	ds_write_b128 v168, v[20:23] offset:20480
	ds_write_b128 v178, v[52:55] offset:20480
	ds_write_b128 v179, v[84:87] offset:20480
	ds_write_b128 v190, v[116:119] offset:20480
	ds_write_b128 v168, v[24:27] offset:24576
	ds_write_b128 v178, v[56:59] offset:24576
	ds_write_b128 v179, v[88:91] offset:24576
	ds_write_b128 v190, v[120:123] offset:24576
	ds_write_b128 v168, v[28:31] offset:28672
	ds_write_b128 v178, v[60:63] offset:28672
	ds_write_b128 v179, v[92:95] offset:28672
	ds_write_b128 v190, v[124:127] offset:28672

.LBB0_717:
	s_add_i32 s1, s0, 0x10000
	s_and_b32 s11, s1, 0x10000
	s_and_b32 s0, s0, 0x10000
	s_add_i32 s0, s0, 16
	v_add_u32_e32 v190, s11, v210
	s_nop 0
	v_readfirstlane_b32 s11, v190
	s_waitcnt vmcnt(0)
	s_barrier
	v_add_u32_e32 v251, s0, v249
	ds_read_b128 v[150:153], v251
	ds_read_b128 v[154:157], v251 offset:2048
	ds_read_b128 v[158:161], v251 offset:4096
	ds_read_b128 v[162:165], v251 offset:6144
	v_add_u32_e32 v250, s0, v248
	ds_read_b128 v[170:173], v250
	ds_read_b128 v[174:177], v250 offset:2048
	ds_read_b128 v[236:239], v250 offset:4096
	ds_read_b128 v[240:243], v250 offset:6144
	v_lshl_add_u64 v[178:179], v[142:143], 0, s[2:3]
	s_mov_b32 m0, s11
	s_nop 0
	global_load_lds_dwordx4 v[178:179], off
	s_waitcnt lgkmcnt(3)
	v_mfma_f32_16x16x32_bf16 v[0:3], v[150:153], v[170:173], v[0:3]
	v_mfma_f32_16x16x32_bf16 v[32:35], v[154:157], v[170:173], v[32:35]
	v_lshl_add_u64 v[178:179], v[140:141], 0, s[2:3]
	s_add_i32 s12, s11, 0x2000
	s_mov_b32 m0, s12
	s_nop 0
	global_load_lds_dwordx4 v[178:179], off
	v_mfma_f32_16x16x32_bf16 v[64:67], v[158:161], v[170:173], v[64:67]
	v_mfma_f32_16x16x32_bf16 v[96:99], v[162:165], v[170:173], v[96:99]
	s_waitcnt lgkmcnt(2)
	v_mfma_f32_16x16x32_bf16 v[4:7], v[150:153], v[174:177], v[4:7]
	v_mfma_f32_16x16x32_bf16 v[36:39], v[154:157], v[174:177], v[36:39]
	v_lshl_add_u64 v[178:179], v[138:139], 0, s[2:3]
	s_add_i32 s12, s11, 0x4000
	s_mov_b32 m0, s12
	s_nop 0
	global_load_lds_dwordx4 v[178:179], off
	v_mfma_f32_16x16x32_bf16 v[68:71], v[158:161], v[174:177], v[68:71]
	v_mfma_f32_16x16x32_bf16 v[100:103], v[162:165], v[174:177], v[100:103]
	s_waitcnt lgkmcnt(1)
	v_mfma_f32_16x16x32_bf16 v[8:11], v[150:153], v[236:239], v[8:11]
	v_mfma_f32_16x16x32_bf16 v[40:43], v[154:157], v[236:239], v[40:43]
	v_lshl_add_u64 v[178:179], v[136:137], 0, s[2:3]
	s_add_i32 s12, s11, 0x6000
	s_mov_b32 m0, s12
	s_nop 0
	global_load_lds_dwordx4 v[178:179], off
	v_mfma_f32_16x16x32_bf16 v[72:75], v[158:161], v[236:239], v[72:75]
	v_mfma_f32_16x16x32_bf16 v[104:107], v[162:165], v[236:239], v[104:107]
	s_waitcnt lgkmcnt(0)
	v_mfma_f32_16x16x32_bf16 v[12:15], v[150:153], v[240:243], v[12:15]
	v_mfma_f32_16x16x32_bf16 v[44:47], v[154:157], v[240:243], v[44:47]
	v_lshl_add_u64 v[178:179], v[134:135], 0, s[2:3]
	s_add_i32 s12, s11, 0x8000
	s_mov_b32 m0, s12
	s_nop 0
	global_load_lds_dwordx4 v[178:179], off
	v_mfma_f32_16x16x32_bf16 v[76:79], v[158:161], v[240:243], v[76:79]
	v_mfma_f32_16x16x32_bf16 v[108:111], v[162:165], v[240:243], v[108:111]
	ds_read_b128 v[170:173], v250 offset:8192
	ds_read_b128 v[174:177], v250 offset:10240
	ds_read_b128 v[236:239], v250 offset:12288
	ds_read_b128 v[240:243], v250 offset:14336
	s_waitcnt lgkmcnt(3)
	v_mfma_f32_16x16x32_bf16 v[16:19], v[150:153], v[170:173], v[16:19]
	v_mfma_f32_16x16x32_bf16 v[48:51], v[154:157], v[170:173], v[48:51]
	v_lshl_add_u64 v[178:179], v[132:133], 0, s[2:3]
	s_add_i32 s12, s11, 0xa000
	s_mov_b32 m0, s12
	s_nop 0
	global_load_lds_dwordx4 v[178:179], off
	v_mfma_f32_16x16x32_bf16 v[80:83], v[158:161], v[170:173], v[80:83]
	v_mfma_f32_16x16x32_bf16 v[112:115], v[162:165], v[170:173], v[112:115]
	s_waitcnt lgkmcnt(2)
	v_mfma_f32_16x16x32_bf16 v[20:23], v[150:153], v[174:177], v[20:23]
	v_mfma_f32_16x16x32_bf16 v[52:55], v[154:157], v[174:177], v[52:55]
	v_lshl_add_u64 v[178:179], v[130:131], 0, s[2:3]
	s_add_i32 s12, s11, 0xc000
	s_mov_b32 m0, s12
	s_nop 0
	global_load_lds_dwordx4 v[178:179], off
	v_mfma_f32_16x16x32_bf16 v[84:87], v[158:161], v[174:177], v[84:87]
	v_mfma_f32_16x16x32_bf16 v[116:119], v[162:165], v[174:177], v[116:119]
	s_waitcnt lgkmcnt(1)
	v_mfma_f32_16x16x32_bf16 v[24:27], v[150:153], v[236:239], v[24:27]
	v_mfma_f32_16x16x32_bf16 v[56:59], v[154:157], v[236:239], v[56:59]
	v_lshl_add_u64 v[178:179], v[128:129], 0, s[2:3]
	s_add_i32 s12, s11, 0xe000
	s_mov_b32 m0, s12
	s_nop 0
	global_load_lds_dwordx4 v[178:179], off
	s_add_u32 s2, s2, 0x80
	s_addc_u32 s3, s3, 0
	s_cmpk_lg_i32 s2, 0x780
	v_mfma_f32_16x16x32_bf16 v[88:91], v[158:161], v[236:239], v[88:91]
	v_mfma_f32_16x16x32_bf16 v[120:123], v[162:165], v[236:239], v[120:123]
	s_waitcnt lgkmcnt(0)
	v_mfma_f32_16x16x32_bf16 v[28:31], v[150:153], v[240:243], v[28:31]
	v_mfma_f32_16x16x32_bf16 v[60:63], v[154:157], v[240:243], v[60:63]
	v_mfma_f32_16x16x32_bf16 v[92:95], v[158:161], v[240:243], v[92:95]
	v_mfma_f32_16x16x32_bf16 v[124:127], v[162:165], v[240:243], v[124:127]
	v_xor_b32_e32 v251, 64, v249
	v_add_u32_e32 v251, s0, v251
	ds_read_b128 v[150:153], v251
	ds_read_b128 v[154:157], v251 offset:2048
	ds_read_b128 v[158:161], v251 offset:4096
	ds_read_b128 v[162:165], v251 offset:6144
	v_xor_b32_e32 v250, 64, v248
	v_add_u32_e32 v250, s0, v250
	ds_read_b128 v[170:173], v250
	ds_read_b128 v[174:177], v250 offset:2048
	ds_read_b128 v[236:239], v250 offset:4096
	ds_read_b128 v[240:243], v250 offset:6144
	s_waitcnt lgkmcnt(3)
	v_mfma_f32_16x16x32_bf16 v[0:3], v[150:153], v[170:173], v[0:3]
	v_mfma_f32_16x16x32_bf16 v[32:35], v[154:157], v[170:173], v[32:35]
	v_mfma_f32_16x16x32_bf16 v[64:67], v[158:161], v[170:173], v[64:67]
	v_mfma_f32_16x16x32_bf16 v[96:99], v[162:165], v[170:173], v[96:99]
	s_waitcnt lgkmcnt(2)
	v_mfma_f32_16x16x32_bf16 v[4:7], v[150:153], v[174:177], v[4:7]
	v_mfma_f32_16x16x32_bf16 v[36:39], v[154:157], v[174:177], v[36:39]
	v_mfma_f32_16x16x32_bf16 v[68:71], v[158:161], v[174:177], v[68:71]
	v_mfma_f32_16x16x32_bf16 v[100:103], v[162:165], v[174:177], v[100:103]
	s_waitcnt lgkmcnt(1)
	v_mfma_f32_16x16x32_bf16 v[8:11], v[150:153], v[236:239], v[8:11]
	v_mfma_f32_16x16x32_bf16 v[40:43], v[154:157], v[236:239], v[40:43]
	v_mfma_f32_16x16x32_bf16 v[72:75], v[158:161], v[236:239], v[72:75]
	v_mfma_f32_16x16x32_bf16 v[104:107], v[162:165], v[236:239], v[104:107]
	s_waitcnt lgkmcnt(0)
	v_mfma_f32_16x16x32_bf16 v[12:15], v[150:153], v[240:243], v[12:15]
	v_mfma_f32_16x16x32_bf16 v[44:47], v[154:157], v[240:243], v[44:47]
	v_mfma_f32_16x16x32_bf16 v[76:79], v[158:161], v[240:243], v[76:79]
	v_mfma_f32_16x16x32_bf16 v[108:111], v[162:165], v[240:243], v[108:111]
	ds_read_b128 v[170:173], v250 offset:8192
	ds_read_b128 v[174:177], v250 offset:10240
	ds_read_b128 v[236:239], v250 offset:12288
	ds_read_b128 v[240:243], v250 offset:14336
	s_waitcnt lgkmcnt(3)
	v_mfma_f32_16x16x32_bf16 v[16:19], v[150:153], v[170:173], v[16:19]
	v_mfma_f32_16x16x32_bf16 v[48:51], v[154:157], v[170:173], v[48:51]
	v_mfma_f32_16x16x32_bf16 v[80:83], v[158:161], v[170:173], v[80:83]
	v_mfma_f32_16x16x32_bf16 v[112:115], v[162:165], v[170:173], v[112:115]
	s_waitcnt lgkmcnt(2)
	v_mfma_f32_16x16x32_bf16 v[20:23], v[150:153], v[174:177], v[20:23]
	v_mfma_f32_16x16x32_bf16 v[52:55], v[154:157], v[174:177], v[52:55]
	v_mfma_f32_16x16x32_bf16 v[84:87], v[158:161], v[174:177], v[84:87]
	v_mfma_f32_16x16x32_bf16 v[116:119], v[162:165], v[174:177], v[116:119]
	s_waitcnt lgkmcnt(1)
	v_mfma_f32_16x16x32_bf16 v[24:27], v[150:153], v[236:239], v[24:27]
	v_mfma_f32_16x16x32_bf16 v[56:59], v[154:157], v[236:239], v[56:59]
	v_mfma_f32_16x16x32_bf16 v[88:91], v[158:161], v[236:239], v[88:91]
	v_mfma_f32_16x16x32_bf16 v[120:123], v[162:165], v[236:239], v[120:123]
	s_waitcnt lgkmcnt(0)
	v_mfma_f32_16x16x32_bf16 v[28:31], v[150:153], v[240:243], v[28:31]
	v_mfma_f32_16x16x32_bf16 v[60:63], v[154:157], v[240:243], v[60:63]
	v_mfma_f32_16x16x32_bf16 v[92:95], v[158:161], v[240:243], v[92:95]
	v_mfma_f32_16x16x32_bf16 v[124:127], v[162:165], v[240:243], v[124:127]
	s_mov_b32 s0, s1
	s_cbranch_scc1 .LBB0_717
	s_add_i32 s21, s21, s78
	s_cmpk_gt_i32 s21, 0xff
	s_waitcnt vmcnt(0)
	s_barrier
	s_cselect_b64 s[2:3], -1, 0
	s_and_b64 vcc, exec, s[2:3]
	s_cbranch_vccnz .LBB0_720
	s_lshl_b32 s0, s21, 3
	s_and_b32 s0, s0, 56
	s_ashr_i32 s1, s21, 5
	s_add_i32 s8, s0, s1
	s_ashr_i32 s0, s8, 5
	s_ashr_i32 s1, s0, 31
	s_lshl_b32 s9, s21, 5
	v_lshl_add_u32 v130, s8, 8, v207
	s_and_b32 s9, s9, 0x300
	s_lshl_b64 s[0:1], s[0:1], 21
	v_ashrrev_i32_e32 v131, 31, v130
	v_lshlrev_b64 v[134:135], 11, v[130:131]
	s_cmp_lg_u32 16, -1
	v_lshl_add_u64 v[128:129], v[144:145], 0, s[0:1]
	v_lshl_add_u64 v[134:135], v[146:147], 0, v[134:135]
	v_readfirstlane_b32 s0, v209
	s_cselect_b32 s1, 16, 0
	s_add_i32 s0, s0, s1
	s_mov_b32 s1, m0
	s_mov_b32 m0, s0
	s_nop 0
	global_load_lds_dwordx4 v[134:135], off
	s_mov_b32 m0, s1
	v_add_u32_e32 v134, 64, v130
	v_ashrrev_i32_e32 v135, 31, v134
	v_lshlrev_b64 v[134:135], 11, v[134:135]
	v_lshl_add_u64 v[134:135], v[146:147], 0, v[134:135]
	s_add_i32 s1, s0, 0x2000
	s_mov_b32 s8, m0
	s_mov_b32 m0, s1
	s_nop 0
	global_load_lds_dwordx4 v[134:135], off
	s_mov_b32 m0, s8
	v_add_u32_e32 v134, 0x80, v130
	v_add_u32_e32 v130, 0xc0, v130
	v_ashrrev_i32_e32 v135, 31, v134
	v_ashrrev_i32_e32 v131, 31, v130
	v_add_u32_e32 v132, s9, v208
	v_lshlrev_b64 v[134:135], 11, v[134:135]
	v_lshlrev_b64 v[130:131], 11, v[130:131]
	v_lshl_add_u64 v[134:135], v[146:147], 0, v[134:135]
	s_add_i32 s1, s0, 0x4000
	s_mov_b32 s8, m0
	s_mov_b32 m0, s1
	s_nop 0
	global_load_lds_dwordx4 v[134:135], off
	s_mov_b32 m0, s8
	v_lshl_add_u64 v[130:131], v[146:147], 0, v[130:131]
	v_ashrrev_i32_e32 v133, 31, v132
	s_add_i32 s1, s0, 0x6000
	s_mov_b32 s8, m0
	s_mov_b32 m0, s1
	s_nop 0
	global_load_lds_dwordx4 v[130:131], off
	s_mov_b32 m0, s8
	v_lshlrev_b64 v[130:131], 11, v[132:133]
	v_lshl_add_u64 v[128:129], v[128:129], 0, v[130:131]
	v_lshl_add_u64 v[130:131], v[128:129], 0, s[34:35]
	s_add_i32 s1, s0, 0x8000
	s_mov_b32 s8, m0
	s_mov_b32 m0, s1
	s_nop 0
	global_load_lds_dwordx4 v[130:131], off
	s_mov_b32 m0, s8
	v_lshl_add_u64 v[130:131], v[128:129], 0, s[38:39]
	s_add_i32 s1, s0, 0xa000
	s_mov_b32 s8, m0
	s_mov_b32 m0, s1
	s_nop 0
	global_load_lds_dwordx4 v[130:131], off
	s_mov_b32 m0, s8
	v_lshl_add_u64 v[130:131], v[128:129], 0, s[36:37]
	s_add_i32 s1, s0, 0xc000
	s_mov_b32 s8, m0
	s_mov_b32 m0, s1
	s_nop 0
	global_load_lds_dwordx4 v[130:131], off
	s_mov_b32 m0, s8
	v_lshl_add_u64 v[128:129], v[128:129], 0, s[40:41]
	s_add_i32 s0, s0, 0xe000
	s_mov_b32 s1, m0
	s_mov_b32 m0, s0
	s_nop 0
	global_load_lds_dwordx4 v[128:129], off
	s_mov_b32 m0, s1
	s_mov_b64 s[8:9], -1
.LBB0_720:
	v_add_u32_e32 v251, 0x10010, v249
	ds_read_b128 v[150:153], v251
	ds_read_b128 v[154:157], v251 offset:2048
	ds_read_b128 v[158:161], v251 offset:4096
	ds_read_b128 v[162:165], v251 offset:6144
	v_add_u32_e32 v250, 0x10010, v248
	ds_read_b128 v[170:173], v250
	ds_read_b128 v[174:177], v250 offset:2048
	ds_read_b128 v[236:239], v250 offset:4096
	ds_read_b128 v[240:243], v250 offset:6144
	s_waitcnt lgkmcnt(3)
	v_mfma_f32_16x16x32_bf16 v[0:3], v[150:153], v[170:173], v[0:3]
	v_mfma_f32_16x16x32_bf16 v[32:35], v[154:157], v[170:173], v[32:35]
	v_mfma_f32_16x16x32_bf16 v[64:67], v[158:161], v[170:173], v[64:67]
	v_mfma_f32_16x16x32_bf16 v[96:99], v[162:165], v[170:173], v[96:99]
	s_waitcnt lgkmcnt(2)
	v_mfma_f32_16x16x32_bf16 v[4:7], v[150:153], v[174:177], v[4:7]
	v_mfma_f32_16x16x32_bf16 v[36:39], v[154:157], v[174:177], v[36:39]
	v_mfma_f32_16x16x32_bf16 v[68:71], v[158:161], v[174:177], v[68:71]
	v_mfma_f32_16x16x32_bf16 v[100:103], v[162:165], v[174:177], v[100:103]
	s_waitcnt lgkmcnt(1)
	v_mfma_f32_16x16x32_bf16 v[8:11], v[150:153], v[236:239], v[8:11]
	v_mfma_f32_16x16x32_bf16 v[40:43], v[154:157], v[236:239], v[40:43]
	v_mfma_f32_16x16x32_bf16 v[72:75], v[158:161], v[236:239], v[72:75]
	v_mfma_f32_16x16x32_bf16 v[104:107], v[162:165], v[236:239], v[104:107]
	s_waitcnt lgkmcnt(0)
	v_mfma_f32_16x16x32_bf16 v[12:15], v[150:153], v[240:243], v[12:15]
	v_mfma_f32_16x16x32_bf16 v[44:47], v[154:157], v[240:243], v[44:47]
	v_mfma_f32_16x16x32_bf16 v[76:79], v[158:161], v[240:243], v[76:79]
	v_mfma_f32_16x16x32_bf16 v[108:111], v[162:165], v[240:243], v[108:111]
	ds_read_b128 v[170:173], v250 offset:8192
	ds_read_b128 v[174:177], v250 offset:10240
	ds_read_b128 v[236:239], v250 offset:12288
	ds_read_b128 v[240:243], v250 offset:14336
	s_waitcnt lgkmcnt(3)
	v_mfma_f32_16x16x32_bf16 v[16:19], v[150:153], v[170:173], v[16:19]
	v_mfma_f32_16x16x32_bf16 v[48:51], v[154:157], v[170:173], v[48:51]
	v_mfma_f32_16x16x32_bf16 v[80:83], v[158:161], v[170:173], v[80:83]
	v_mfma_f32_16x16x32_bf16 v[112:115], v[162:165], v[170:173], v[112:115]
	s_waitcnt lgkmcnt(2)
	v_mfma_f32_16x16x32_bf16 v[20:23], v[150:153], v[174:177], v[20:23]
	v_mfma_f32_16x16x32_bf16 v[52:55], v[154:157], v[174:177], v[52:55]
	v_mfma_f32_16x16x32_bf16 v[84:87], v[158:161], v[174:177], v[84:87]
	v_mfma_f32_16x16x32_bf16 v[116:119], v[162:165], v[174:177], v[116:119]
	s_waitcnt lgkmcnt(1)
	v_mfma_f32_16x16x32_bf16 v[24:27], v[150:153], v[236:239], v[24:27]
	v_mfma_f32_16x16x32_bf16 v[56:59], v[154:157], v[236:239], v[56:59]
	v_mfma_f32_16x16x32_bf16 v[88:91], v[158:161], v[236:239], v[88:91]
	v_mfma_f32_16x16x32_bf16 v[120:123], v[162:165], v[236:239], v[120:123]
	s_waitcnt lgkmcnt(0)
	v_mfma_f32_16x16x32_bf16 v[28:31], v[150:153], v[240:243], v[28:31]
	v_mfma_f32_16x16x32_bf16 v[60:63], v[154:157], v[240:243], v[60:63]
	v_mfma_f32_16x16x32_bf16 v[92:95], v[158:161], v[240:243], v[92:95]
	v_mfma_f32_16x16x32_bf16 v[124:127], v[162:165], v[240:243], v[124:127]
	v_xor_b32_e32 v251, 64, v249
	v_add_u32_e32 v251, 0x10010, v251
	ds_read_b128 v[150:153], v251
	ds_read_b128 v[154:157], v251 offset:2048
	ds_read_b128 v[158:161], v251 offset:4096
	ds_read_b128 v[162:165], v251 offset:6144
	v_xor_b32_e32 v250, 64, v248
	v_add_u32_e32 v250, 0x10010, v250
	ds_read_b128 v[170:173], v250
	ds_read_b128 v[174:177], v250 offset:2048
	ds_read_b128 v[236:239], v250 offset:4096
	ds_read_b128 v[240:243], v250 offset:6144
	s_waitcnt lgkmcnt(3)
	v_mfma_f32_16x16x32_bf16 v[0:3], v[150:153], v[170:173], v[0:3]
	v_mfma_f32_16x16x32_bf16 v[32:35], v[154:157], v[170:173], v[32:35]
	v_mfma_f32_16x16x32_bf16 v[64:67], v[158:161], v[170:173], v[64:67]
	v_mfma_f32_16x16x32_bf16 v[96:99], v[162:165], v[170:173], v[96:99]
	s_waitcnt lgkmcnt(2)
	v_mfma_f32_16x16x32_bf16 v[4:7], v[150:153], v[174:177], v[4:7]
	v_mfma_f32_16x16x32_bf16 v[36:39], v[154:157], v[174:177], v[36:39]
	v_mfma_f32_16x16x32_bf16 v[68:71], v[158:161], v[174:177], v[68:71]
	v_mfma_f32_16x16x32_bf16 v[100:103], v[162:165], v[174:177], v[100:103]
	s_waitcnt lgkmcnt(1)
	v_mfma_f32_16x16x32_bf16 v[8:11], v[150:153], v[236:239], v[8:11]
	v_mfma_f32_16x16x32_bf16 v[40:43], v[154:157], v[236:239], v[40:43]
	v_mfma_f32_16x16x32_bf16 v[72:75], v[158:161], v[236:239], v[72:75]
	v_mfma_f32_16x16x32_bf16 v[104:107], v[162:165], v[236:239], v[104:107]
	s_waitcnt lgkmcnt(0)
	v_mfma_f32_16x16x32_bf16 v[12:15], v[150:153], v[240:243], v[12:15]
	v_mfma_f32_16x16x32_bf16 v[44:47], v[154:157], v[240:243], v[44:47]
	v_mfma_f32_16x16x32_bf16 v[76:79], v[158:161], v[240:243], v[76:79]
	v_mfma_f32_16x16x32_bf16 v[108:111], v[162:165], v[240:243], v[108:111]
	ds_read_b128 v[170:173], v250 offset:8192
	ds_read_b128 v[174:177], v250 offset:10240
	ds_read_b128 v[236:239], v250 offset:12288
	ds_read_b128 v[240:243], v250 offset:14336
	s_waitcnt lgkmcnt(0)
	s_barrier
	v_mfma_f32_16x16x32_bf16 v[16:19], v[150:153], v[170:173], v[16:19]
	v_mfma_f32_16x16x32_bf16 v[48:51], v[154:157], v[170:173], v[48:51]
	v_mfma_f32_16x16x32_bf16 v[80:83], v[158:161], v[170:173], v[80:83]
	v_mfma_f32_16x16x32_bf16 v[112:115], v[162:165], v[170:173], v[112:115]
	v_mfma_f32_16x16x32_bf16 v[20:23], v[150:153], v[174:177], v[20:23]
	v_mfma_f32_16x16x32_bf16 v[52:55], v[154:157], v[174:177], v[52:55]
	v_mfma_f32_16x16x32_bf16 v[84:87], v[158:161], v[174:177], v[84:87]
	v_mfma_f32_16x16x32_bf16 v[116:119], v[162:165], v[174:177], v[116:119]
	v_mfma_f32_16x16x32_bf16 v[24:27], v[150:153], v[236:239], v[24:27]
	v_mfma_f32_16x16x32_bf16 v[56:59], v[154:157], v[236:239], v[56:59]
	v_mfma_f32_16x16x32_bf16 v[88:91], v[158:161], v[236:239], v[88:91]
	v_mfma_f32_16x16x32_bf16 v[120:123], v[162:165], v[236:239], v[120:123]
	v_mfma_f32_16x16x32_bf16 v[28:31], v[150:153], v[240:243], v[28:31]
	v_mfma_f32_16x16x32_bf16 v[60:63], v[154:157], v[240:243], v[60:63]
	v_mfma_f32_16x16x32_bf16 v[92:95], v[158:161], v[240:243], v[92:95]
	v_mfma_f32_16x16x32_bf16 v[124:127], v[162:165], v[240:243], v[124:127]
	s_lshl_b32 s52, s10, 2
	s_lshr_b32 s0, s10, 4
	s_add_u32 s0, s18, s0
	v_or_b32_e32 v236, s10, v213
	v_lshl_add_u64 v[166:167], v[148:149], 0, s[52:53]
	s_addc_u32 s1, s19, 0
	s_mov_b32 s10, 0
	v_or_b32_e32 v128, s22, v212
	v_add_u32_e32 v128, v128, v211
	v_add_u32_e32 v130, 16, v128
	v_ashrrev_i32_e32 v131, 31, v130
	v_lshlrev_b64 v[158:159], 12, v[130:131]
	v_add_u32_e32 v130, 20, v128
	v_ashrrev_i32_e32 v129, 31, v128
	v_ashrrev_i32_e32 v131, 31, v130
	v_lshlrev_b64 v[160:161], 12, v[130:131]
	v_add_u32_e32 v130, 24, v128
	v_ashrrev_i32_e32 v131, 31, v130
	v_lshlrev_b64 v[162:163], 12, v[130:131]
	v_lshlrev_b64 v[150:151], 12, v[128:129]
	v_or_b32_e32 v132, 4, v128
	v_ashrrev_i32_e32 v133, 31, v132
	v_lshlrev_b64 v[152:153], 12, v[132:133]
	v_or_b32_e32 v132, 8, v128
	v_ashrrev_i32_e32 v133, 31, v132
	v_lshlrev_b64 v[154:155], 12, v[132:133]
	v_or_b32_e32 v132, 12, v128
	v_add_u32_e32 v128, 28, v128
	v_ashrrev_i32_e32 v133, 31, v132
	v_ashrrev_i32_e32 v129, 31, v128
	v_lshlrev_b64 v[156:157], 12, v[132:133]
	v_lshlrev_b64 v[164:165], 12, v[128:129]
	s_branch .LBB0_722

.LBB0_722:
	s_lshl_b32 s52, s10, 6
	v_lshl_add_u64 v[176:177], s[52:53], 2, v[166:167]
	v_lshl_add_u64 v[128:129], v[176:177], 0, v[150:151]
	v_lshl_add_u64 v[132:133], v[176:177], 0, v[152:153]
	v_lshl_add_u64 v[136:137], v[176:177], 0, v[154:155]
	v_lshl_add_u64 v[140:141], v[176:177], 0, v[156:157]
	global_load_dwordx4 v[128:131], v[128:129], off
	s_nop 0
	global_load_dwordx4 v[132:135], v[132:133], off
	s_nop 0
	global_load_dwordx4 v[136:139], v[136:137], off
	s_nop 0
	global_load_dwordx4 v[140:143], v[140:141], off
	v_cmp_eq_u32_e32 vcc, s10, v181
	s_and_saveexec_b64 s[12:13], vcc
	s_cbranch_execz .LBB0_724
	v_and_b32_e32 v237, 15, v184
	v_bfe_u32 v238, v184, 4, 2
	v_lshrrev_b32_e32 v239, 8, v184
	v_lshlrev_b32_e32 v240, 8, v237
	v_lshl_add_u32 v240, v239, 15, v240
	v_add_u32_e32 v240, 0x10010, v240
	v_or_b32_e32 v241, 0, v238
	v_xor_b32_e32 v241, v241, v237
	v_lshl_add_u32 v168, v241, 4, v240
	v_or_b32_e32 v241, 4, v238
	v_xor_b32_e32 v241, v241, v237
	v_lshl_add_u32 v178, v241, 4, v240
	v_or_b32_e32 v241, 8, v238
	v_xor_b32_e32 v241, v241, v237
	v_lshl_add_u32 v179, v241, 4, v240
	v_or_b32_e32 v241, 12, v238
	v_xor_b32_e32 v241, v241, v237
	v_lshl_add_u32 v190, v241, 4, v240
	ds_write_b128 v168, v[0:3]
	ds_write_b128 v178, v[32:35]
	ds_write_b128 v179, v[64:67]
	ds_write_b128 v190, v[96:99]
	ds_write_b128 v168, v[4:7] offset:4096
	ds_write_b128 v178, v[36:39] offset:4096
	ds_write_b128 v179, v[68:71] offset:4096
	ds_write_b128 v190, v[100:103] offset:4096
	ds_write_b128 v168, v[8:11] offset:8192
	ds_write_b128 v178, v[40:43] offset:8192
	ds_write_b128 v179, v[72:75] offset:8192
	ds_write_b128 v190, v[104:107] offset:8192
	ds_write_b128 v168, v[12:15] offset:12288
	ds_write_b128 v178, v[44:47] offset:12288
	ds_write_b128 v179, v[76:79] offset:12288
	ds_write_b128 v190, v[108:111] offset:12288
	ds_write_b128 v168, v[16:19] offset:16384
	ds_write_b128 v178, v[48:51] offset:16384
	ds_write_b128 v179, v[80:83] offset:16384
	ds_write_b128 v190, v[112:115] offset:16384
	ds_write_b128 v168, v[20:23] offset:20480
	ds_write_b128 v178, v[52:55] offset:20480
	ds_write_b128 v179, v[84:87] offset:20480
	ds_write_b128 v190, v[116:119] offset:20480
	ds_write_b128 v168, v[24:27] offset:24576
	ds_write_b128 v178, v[56:59] offset:24576
	ds_write_b128 v179, v[88:91] offset:24576
	ds_write_b128 v190, v[120:123] offset:24576
	ds_write_b128 v168, v[28:31] offset:28672
	ds_write_b128 v178, v[60:63] offset:28672
	ds_write_b128 v179, v[92:95] offset:28672
	ds_write_b128 v190, v[124:127] offset:28672

.LBB0_778:
	s_add_i32 s1, s0, 0x10000
	s_and_b32 s11, s1, 0x10000
	s_and_b32 s0, s0, 0x10000
	s_add_i32 s0, s0, 16
	v_add_u32_e32 v190, s11, v210
	s_nop 0
	v_readfirstlane_b32 s11, v190
	s_waitcnt vmcnt(0)
	s_barrier
	v_add_u32_e32 v251, s0, v249
	ds_read_b128 v[150:153], v251
	ds_read_b128 v[154:157], v251 offset:2048
	ds_read_b128 v[158:161], v251 offset:4096
	ds_read_b128 v[162:165], v251 offset:6144
	v_add_u32_e32 v250, s0, v248
	ds_read_b128 v[170:173], v250
	ds_read_b128 v[174:177], v250 offset:2048
	ds_read_b128 v[236:239], v250 offset:4096
	ds_read_b128 v[240:243], v250 offset:6144
	v_lshl_add_u64 v[178:179], v[142:143], 0, s[2:3]
	s_mov_b32 m0, s11
	s_nop 0
	global_load_lds_dwordx4 v[178:179], off
	s_waitcnt lgkmcnt(3)
	v_mfma_f32_16x16x32_bf16 v[0:3], v[150:153], v[170:173], v[0:3]
	v_mfma_f32_16x16x32_bf16 v[32:35], v[154:157], v[170:173], v[32:35]
	v_lshl_add_u64 v[178:179], v[140:141], 0, s[2:3]
	s_add_i32 s12, s11, 0x2000
	s_mov_b32 m0, s12
	s_nop 0
	global_load_lds_dwordx4 v[178:179], off
	v_mfma_f32_16x16x32_bf16 v[64:67], v[158:161], v[170:173], v[64:67]
	v_mfma_f32_16x16x32_bf16 v[96:99], v[162:165], v[170:173], v[96:99]
	s_waitcnt lgkmcnt(2)
	v_mfma_f32_16x16x32_bf16 v[4:7], v[150:153], v[174:177], v[4:7]
	v_mfma_f32_16x16x32_bf16 v[36:39], v[154:157], v[174:177], v[36:39]
	v_lshl_add_u64 v[178:179], v[138:139], 0, s[2:3]
	s_add_i32 s12, s11, 0x4000
	s_mov_b32 m0, s12
	s_nop 0
	global_load_lds_dwordx4 v[178:179], off
	v_mfma_f32_16x16x32_bf16 v[68:71], v[158:161], v[174:177], v[68:71]
	v_mfma_f32_16x16x32_bf16 v[100:103], v[162:165], v[174:177], v[100:103]
	s_waitcnt lgkmcnt(1)
	v_mfma_f32_16x16x32_bf16 v[8:11], v[150:153], v[236:239], v[8:11]
	v_mfma_f32_16x16x32_bf16 v[40:43], v[154:157], v[236:239], v[40:43]
	v_lshl_add_u64 v[178:179], v[136:137], 0, s[2:3]
	s_add_i32 s12, s11, 0x6000
	s_mov_b32 m0, s12
	s_nop 0
	global_load_lds_dwordx4 v[178:179], off
	v_mfma_f32_16x16x32_bf16 v[72:75], v[158:161], v[236:239], v[72:75]
	v_mfma_f32_16x16x32_bf16 v[104:107], v[162:165], v[236:239], v[104:107]
	s_waitcnt lgkmcnt(0)
	v_mfma_f32_16x16x32_bf16 v[12:15], v[150:153], v[240:243], v[12:15]
	v_mfma_f32_16x16x32_bf16 v[44:47], v[154:157], v[240:243], v[44:47]
	v_lshl_add_u64 v[178:179], v[134:135], 0, s[2:3]
	s_add_i32 s12, s11, 0x8000
	s_mov_b32 m0, s12
	s_nop 0
	global_load_lds_dwordx4 v[178:179], off
	v_mfma_f32_16x16x32_bf16 v[76:79], v[158:161], v[240:243], v[76:79]
	v_mfma_f32_16x16x32_bf16 v[108:111], v[162:165], v[240:243], v[108:111]
	ds_read_b128 v[170:173], v250 offset:8192
	ds_read_b128 v[174:177], v250 offset:10240
	ds_read_b128 v[236:239], v250 offset:12288
	ds_read_b128 v[240:243], v250 offset:14336
	s_waitcnt lgkmcnt(3)
	v_mfma_f32_16x16x32_bf16 v[16:19], v[150:153], v[170:173], v[16:19]
	v_mfma_f32_16x16x32_bf16 v[48:51], v[154:157], v[170:173], v[48:51]
	v_lshl_add_u64 v[178:179], v[132:133], 0, s[2:3]
	s_add_i32 s12, s11, 0xa000
	s_mov_b32 m0, s12
	s_nop 0
	global_load_lds_dwordx4 v[178:179], off
	v_mfma_f32_16x16x32_bf16 v[80:83], v[158:161], v[170:173], v[80:83]
	v_mfma_f32_16x16x32_bf16 v[112:115], v[162:165], v[170:173], v[112:115]
	s_waitcnt lgkmcnt(2)
	v_mfma_f32_16x16x32_bf16 v[20:23], v[150:153], v[174:177], v[20:23]
	v_mfma_f32_16x16x32_bf16 v[52:55], v[154:157], v[174:177], v[52:55]
	v_lshl_add_u64 v[178:179], v[130:131], 0, s[2:3]
	s_add_i32 s12, s11, 0xc000
	s_mov_b32 m0, s12
	s_nop 0
	global_load_lds_dwordx4 v[178:179], off
	v_mfma_f32_16x16x32_bf16 v[84:87], v[158:161], v[174:177], v[84:87]
	v_mfma_f32_16x16x32_bf16 v[116:119], v[162:165], v[174:177], v[116:119]
	s_waitcnt lgkmcnt(1)
	v_mfma_f32_16x16x32_bf16 v[24:27], v[150:153], v[236:239], v[24:27]
	v_mfma_f32_16x16x32_bf16 v[56:59], v[154:157], v[236:239], v[56:59]
	v_lshl_add_u64 v[178:179], v[128:129], 0, s[2:3]
	s_add_i32 s12, s11, 0xe000
	s_mov_b32 m0, s12
	s_nop 0
	global_load_lds_dwordx4 v[178:179], off
	s_add_u32 s2, s2, 0x80
	s_addc_u32 s3, s3, 0
	s_cmpk_lg_i32 s2, 0x780
	v_mfma_f32_16x16x32_bf16 v[88:91], v[158:161], v[236:239], v[88:91]
	v_mfma_f32_16x16x32_bf16 v[120:123], v[162:165], v[236:239], v[120:123]
	s_waitcnt lgkmcnt(0)
	v_mfma_f32_16x16x32_bf16 v[28:31], v[150:153], v[240:243], v[28:31]
	v_mfma_f32_16x16x32_bf16 v[60:63], v[154:157], v[240:243], v[60:63]
	v_mfma_f32_16x16x32_bf16 v[92:95], v[158:161], v[240:243], v[92:95]
	v_mfma_f32_16x16x32_bf16 v[124:127], v[162:165], v[240:243], v[124:127]
	v_xor_b32_e32 v251, 64, v249
	v_add_u32_e32 v251, s0, v251
	ds_read_b128 v[150:153], v251
	ds_read_b128 v[154:157], v251 offset:2048
	ds_read_b128 v[158:161], v251 offset:4096
	ds_read_b128 v[162:165], v251 offset:6144
	v_xor_b32_e32 v250, 64, v248
	v_add_u32_e32 v250, s0, v250
	ds_read_b128 v[170:173], v250
	ds_read_b128 v[174:177], v250 offset:2048
	ds_read_b128 v[236:239], v250 offset:4096
	ds_read_b128 v[240:243], v250 offset:6144
	s_waitcnt lgkmcnt(3)
	v_mfma_f32_16x16x32_bf16 v[0:3], v[150:153], v[170:173], v[0:3]
	v_mfma_f32_16x16x32_bf16 v[32:35], v[154:157], v[170:173], v[32:35]
	v_mfma_f32_16x16x32_bf16 v[64:67], v[158:161], v[170:173], v[64:67]
	v_mfma_f32_16x16x32_bf16 v[96:99], v[162:165], v[170:173], v[96:99]
	s_waitcnt lgkmcnt(2)
	v_mfma_f32_16x16x32_bf16 v[4:7], v[150:153], v[174:177], v[4:7]
	v_mfma_f32_16x16x32_bf16 v[36:39], v[154:157], v[174:177], v[36:39]
	v_mfma_f32_16x16x32_bf16 v[68:71], v[158:161], v[174:177], v[68:71]
	v_mfma_f32_16x16x32_bf16 v[100:103], v[162:165], v[174:177], v[100:103]
	s_waitcnt lgkmcnt(1)
	v_mfma_f32_16x16x32_bf16 v[8:11], v[150:153], v[236:239], v[8:11]
	v_mfma_f32_16x16x32_bf16 v[40:43], v[154:157], v[236:239], v[40:43]
	v_mfma_f32_16x16x32_bf16 v[72:75], v[158:161], v[236:239], v[72:75]
	v_mfma_f32_16x16x32_bf16 v[104:107], v[162:165], v[236:239], v[104:107]
	s_waitcnt lgkmcnt(0)
	v_mfma_f32_16x16x32_bf16 v[12:15], v[150:153], v[240:243], v[12:15]
	v_mfma_f32_16x16x32_bf16 v[44:47], v[154:157], v[240:243], v[44:47]
	v_mfma_f32_16x16x32_bf16 v[76:79], v[158:161], v[240:243], v[76:79]
	v_mfma_f32_16x16x32_bf16 v[108:111], v[162:165], v[240:243], v[108:111]
	ds_read_b128 v[170:173], v250 offset:8192
	ds_read_b128 v[174:177], v250 offset:10240
	ds_read_b128 v[236:239], v250 offset:12288
	ds_read_b128 v[240:243], v250 offset:14336
	s_waitcnt lgkmcnt(3)
	v_mfma_f32_16x16x32_bf16 v[16:19], v[150:153], v[170:173], v[16:19]
	v_mfma_f32_16x16x32_bf16 v[48:51], v[154:157], v[170:173], v[48:51]
	v_mfma_f32_16x16x32_bf16 v[80:83], v[158:161], v[170:173], v[80:83]
	v_mfma_f32_16x16x32_bf16 v[112:115], v[162:165], v[170:173], v[112:115]
	s_waitcnt lgkmcnt(2)
	v_mfma_f32_16x16x32_bf16 v[20:23], v[150:153], v[174:177], v[20:23]
	v_mfma_f32_16x16x32_bf16 v[52:55], v[154:157], v[174:177], v[52:55]
	v_mfma_f32_16x16x32_bf16 v[84:87], v[158:161], v[174:177], v[84:87]
	v_mfma_f32_16x16x32_bf16 v[116:119], v[162:165], v[174:177], v[116:119]
	s_waitcnt lgkmcnt(1)
	v_mfma_f32_16x16x32_bf16 v[24:27], v[150:153], v[236:239], v[24:27]
	v_mfma_f32_16x16x32_bf16 v[56:59], v[154:157], v[236:239], v[56:59]
	v_mfma_f32_16x16x32_bf16 v[88:91], v[158:161], v[236:239], v[88:91]
	v_mfma_f32_16x16x32_bf16 v[120:123], v[162:165], v[236:239], v[120:123]
	s_waitcnt lgkmcnt(0)
	v_mfma_f32_16x16x32_bf16 v[28:31], v[150:153], v[240:243], v[28:31]
	v_mfma_f32_16x16x32_bf16 v[60:63], v[154:157], v[240:243], v[60:63]
	v_mfma_f32_16x16x32_bf16 v[92:95], v[158:161], v[240:243], v[92:95]
	v_mfma_f32_16x16x32_bf16 v[124:127], v[162:165], v[240:243], v[124:127]
	s_mov_b32 s0, s1
	s_cbranch_scc1 .LBB0_778
	s_add_i32 s21, s21, s78
	s_cmpk_gt_i32 s21, 0xff
	s_waitcnt vmcnt(0)
	s_barrier
	s_cselect_b64 s[2:3], -1, 0
	s_and_b64 vcc, exec, s[2:3]
	s_cbranch_vccnz .LBB0_781
	s_lshl_b32 s0, s21, 3
	s_lshr_b32 s1, s21, 5
	s_and_b32 s0, s0, 56
	s_add_i32 s0, s0, s1
	s_lshl_b32 s8, s21, 5
	v_lshl_add_u32 v130, s0, 8, v207
	s_and_b32 s8, s8, 0x300
	v_ashrrev_i32_e32 v131, 31, v130
	v_lshlrev_b64 v[132:133], 11, v[130:131]
	s_cmp_lg_u32 16, -1
	v_lshl_add_u64 v[132:133], v[146:147], 0, v[132:133]
	v_readfirstlane_b32 s0, v209
	s_cselect_b32 s1, 16, 0
	s_add_i32 s0, s0, s1
	s_mov_b32 s1, m0
	s_mov_b32 m0, s0
	s_nop 0
	global_load_lds_dwordx4 v[132:133], off
	s_mov_b32 m0, s1
	v_add_u32_e32 v132, 64, v130
	v_ashrrev_i32_e32 v133, 31, v132
	v_lshlrev_b64 v[132:133], 11, v[132:133]
	v_lshl_add_u64 v[132:133], v[146:147], 0, v[132:133]
	v_add_u32_e32 v128, s8, v208
	s_add_i32 s1, s0, 0x2000
	s_mov_b32 s8, m0
	s_mov_b32 m0, s1
	s_nop 0
	global_load_lds_dwordx4 v[132:133], off
	s_mov_b32 m0, s8
	v_add_u32_e32 v132, 0x80, v130
	v_ashrrev_i32_e32 v133, 31, v132
	v_add_u32_e32 v130, 0xc0, v130
	v_lshlrev_b64 v[132:133], 11, v[132:133]
	v_ashrrev_i32_e32 v131, 31, v130
	v_ashrrev_i32_e32 v129, 31, v128
	v_lshl_add_u64 v[132:133], v[146:147], 0, v[132:133]
	s_add_i32 s1, s0, 0x4000
	s_mov_b32 s8, m0
	s_mov_b32 m0, s1
	s_nop 0
	global_load_lds_dwordx4 v[132:133], off
	s_mov_b32 m0, s8
	v_lshlrev_b64 v[130:131], 11, v[130:131]
	v_lshlrev_b64 v[128:129], 11, v[128:129]
	v_lshl_add_u64 v[130:131], v[146:147], 0, v[130:131]
	s_add_i32 s1, s0, 0x6000
	s_mov_b32 s8, m0
	s_mov_b32 m0, s1
	s_nop 0
	global_load_lds_dwordx4 v[130:131], off
	s_mov_b32 m0, s8
	v_lshl_add_u64 v[128:129], v[144:145], 0, v[128:129]
	v_lshl_add_u64 v[130:131], v[128:129], 0, s[34:35]
	s_add_i32 s1, s0, 0x8000
	s_mov_b32 s8, m0
	s_mov_b32 m0, s1
	s_nop 0
	global_load_lds_dwordx4 v[130:131], off
	s_mov_b32 m0, s8
	v_lshl_add_u64 v[130:131], v[128:129], 0, s[38:39]
	s_add_i32 s1, s0, 0xa000
	s_mov_b32 s8, m0
	s_mov_b32 m0, s1
	s_nop 0
	global_load_lds_dwordx4 v[130:131], off
	s_mov_b32 m0, s8
	v_lshl_add_u64 v[130:131], v[128:129], 0, s[36:37]
	s_add_i32 s1, s0, 0xc000
	s_mov_b32 s8, m0
	s_mov_b32 m0, s1
	s_nop 0
	global_load_lds_dwordx4 v[130:131], off
	s_mov_b32 m0, s8
	v_lshl_add_u64 v[128:129], v[128:129], 0, s[40:41]
	s_add_i32 s0, s0, 0xe000
	s_mov_b32 s1, m0
	s_mov_b32 m0, s0
	s_nop 0
	global_load_lds_dwordx4 v[128:129], off
	s_mov_b32 m0, s1
	s_mov_b64 s[8:9], -1
